# P0 row loop: next row of x prefetched into spare VGPRs while the current row is normalised (counted vmcnt), loop-invariant gate-bias loads hoisted out of the loop
# baseline (speedup 1.0000x reference)
; #define LAS __attribute__((address_space(3)))
; __device__ __forceinline__ unsigned pk2(float lo, float hi) { const f32x2v v = {lo, hi}; return __builtin_bit_cast(unsigned, __builtin_convertvector(v, bf16x2_hw)); }
; __device__ __forceinline__ void phase0(const Params& P, LAS unsigned char* lds, int G) {
;     ...
;         for (int row = gw; row < MT; row += NGW) {
;             const float* xr = row < MP ? xp + (size_t)row * DM : xs + (size_t)(row - MP) * DM;
;             f32x4v v[4]; float s = 0.f;
; #pragma unroll
;             for (int j = 0; j < 4; ++j) { v[j] = *(const f32x4v*)(xr + 256 * j + 4 * lane); s += (v[j][0] * v[j][0] + v[j][1] * v[j][1]) + (v[j][2] * v[j][2] + v[j][3] * v[j][3]); }
;             const float rs = 1.0f / sqrtf(wave_sum(s) * (1.0f / DM) + EPSN);
; #pragma unroll
;             for (int j = 0; j < 4; ++j) { v[j] = v[j] * rs; u32x2v w; w.x = pk2(v[j][0], v[j][1]); w.y = pk2(v[j][2], v[j][3]); *(u32x2v*)(XN + (size_t)row * DM + 256 * j + 4 * lane) = w; }
;             float d[8];
; #pragma unroll
;             for (int gi = 0; gi < 8; ++gi) {
;                 float s_ = 0.f;
; #pragma unroll
;                 for (int j = 0; j < 4; ++j) { const f32x4v w = *(const LAS f32x4v*)(wg + gi * 1024 + 256 * j + 4 * lane); s_ += (v[j][0] * w[0] + v[j][1] * w[1]) + (v[j][2] * w[2] + v[j][3] * w[3]); }
.LBB0_28:
	s_or_b64 exec, exec, s[8:9]
	v_ashrrev_i32_e32 v0, 6, v150
	v_add_u32_e32 v148, s1, v0
	s_movk_i32 s4, 0x4020
	v_cmp_gt_i32_e32 vcc, s4, v148
	s_waitcnt lgkmcnt(0)
	s_barrier
	s_and_saveexec_b64 s[68:69], vcc
	s_cbranch_execz .LBB0_43
	v_and_b32_e32 v1, 64, v173
	v_add_u32_e32 v1, 64, v1
	v_xor_b32_e32 v2, 1, v173
	v_cmp_lt_i32_e32 vcc, v2, v1
	v_and_b32_e32 v0, 63, v150
	v_lshlrev_b32_e32 v128, 2, v0
	v_cndmask_b32_e32 v2, v173, v2, vcc
	v_lshlrev_b32_e32 v151, 2, v2
	v_xor_b32_e32 v2, 2, v173
	v_cmp_lt_i32_e32 vcc, v2, v1
	v_lshlrev_b32_e32 v144, 3, v0
	v_cmp_gt_u32_e64 s[10:11], 8, v0
	v_cndmask_b32_e32 v2, v173, v2, vcc
	v_lshlrev_b32_e32 v181, 2, v2
	v_xor_b32_e32 v2, 4, v173
	v_cmp_lt_i32_e32 vcc, v2, v1
	v_lshl_add_u64 v[152:153], s[42:43], 0, v[144:145]
	v_ashrrev_i32_e32 v149, 31, v148
	v_cndmask_b32_e32 v2, v173, v2, vcc
	v_lshlrev_b32_e32 v182, 2, v2
	v_xor_b32_e32 v2, 8, v173
	v_cmp_lt_i32_e32 vcc, v2, v1
	v_lshlrev_b64 v[130:131], 12, v[148:149]
	v_lshl_add_u64 v[160:161], s[28:29], 0, v[130:131]
	v_cndmask_b32_e32 v2, v173, v2, vcc
	v_lshlrev_b32_e32 v183, 2, v2
	v_xor_b32_e32 v2, 16, v173
	v_cmp_lt_i32_e32 vcc, v2, v1
	s_mov_b64 s[70:71], 0
	v_mov_b64_e32 v[162:163], v[148:149]
	v_cndmask_b32_e32 v2, v173, v2, vcc
	v_lshlrev_b32_e32 v184, 2, v2
	v_xor_b32_e32 v2, 32, v173
	v_cmp_lt_i32_e32 vcc, v2, v1
	s_nop 1
	v_cndmask_b32_e32 v1, v173, v2, vcc
	v_lshlrev_b32_e32 v185, 2, v1
	v_lshl_add_u32 v1, v0, 4, 0
	v_add_u32_e32 v124, 0x12000, v1
	v_and_b32_e32 v1, 1, v150
	v_cmp_eq_u32_e64 s[4:5], 0, v1
	v_and_b32_e32 v1, 2, v150
	v_cmp_eq_u32_e64 s[6:7], 0, v1
	v_and_b32_e32 v1, 4, v150
	v_bfrev_b32_e32 v0, v150
	v_cmp_eq_u32_e64 s[8:9], 0, v1
	v_ashrrev_i16_sdwa v1, v174, v0 dst_sel:DWORD dst_unused:UNUSED_PAD src0_sel:DWORD src1_sel:WORD_1
	v_lshrrev_b32_e32 v0, 27, v0
	v_cmp_gt_i16_e64 s[12:13], 0, v1
	v_and_b32_e32 v144, 28, v0
	ds_read_b128 v[0:3], v124
	ds_read_b128 v[4:7], v124 offset:1024
	ds_read_b128 v[8:11], v124 offset:2048
	ds_read_b128 v[12:15], v124 offset:3072
	ds_read_b128 v[16:19], v124 offset:4096
	ds_read_b128 v[20:23], v124 offset:5120
	ds_read_b128 v[24:27], v124 offset:6144
	ds_read_b128 v[28:31], v124 offset:7168
	ds_read_b128 v[32:35], v124 offset:8192
	ds_read_b128 v[36:39], v124 offset:9216
	ds_read_b128 v[40:43], v124 offset:10240
	ds_read_b128 v[44:47], v124 offset:11264
	ds_read_b128 v[48:51], v124 offset:12288
	ds_read_b128 v[52:55], v124 offset:13312
	ds_read_b128 v[56:59], v124 offset:14336
	ds_read_b128 v[60:63], v124 offset:15360
	ds_read_b128 v[64:67], v124 offset:16384
	ds_read_b128 v[68:71], v124 offset:17408
	ds_read_b128 v[72:75], v124 offset:18432
	ds_read_b128 v[76:79], v124 offset:19456
	ds_read_b128 v[80:83], v124 offset:20480
	ds_read_b128 v[84:87], v124 offset:21504
	ds_read_b128 v[88:91], v124 offset:22528
	ds_read_b128 v[92:95], v124 offset:23552
	ds_read_b128 v[96:99], v124 offset:24576
	ds_read_b128 v[100:103], v124 offset:25600
	ds_read_b128 v[104:107], v124 offset:26624
	ds_read_b128 v[108:111], v124 offset:27648
	ds_read_b128 v[112:115], v124 offset:28672
	ds_read_b128 v[116:119], v124 offset:29696
	ds_read_b128 v[120:123], v124 offset:30720
	ds_read_b128 v[124:127], v124 offset:31744
	v_lshl_add_u64 v[154:155], s[38:39], 0, v[144:145]
	v_lshl_add_u64 v[156:157], s[40:41], 0, v[144:145]
	v_lshl_add_u64 v[158:159], s[36:37], 0, v[144:145]
	v_lshlrev_b32_e32 v144, 2, v128
	s_and_b64 s[72:73], s[10:11], s[12:13]
	s_andn2_b64 s[74:75], s[10:11], s[12:13]
	s_mov_b64 s[16:17], exec
	s_and_b64 exec, s[16:17], s[72:73]
	s_cbranch_execz .Lp0row_b1
	global_load_dword v224, v[154:155], off offset:-16
.Lp0row_b1:
	s_and_b64 exec, s[16:17], s[74:75]
	s_cbranch_execz .Lp0row_b2
	global_load_dword v225, v[158:159], off
.Lp0row_b2:
	s_mov_b64 exec, s[16:17]
	v_cmp_lt_i32_e32 vcc, s87, v162
	v_mov_b64_e32 v[226:227], v[160:161]
	s_and_saveexec_b64 s[16:17], vcc
	v_add_u32_e32 v226, 0xffffc000, v162
	v_mov_b32_e32 v227, v145
	v_lshlrev_b64 v[226:227], 12, v[226:227]
	v_lshl_add_u64 v[226:227], s[30:31], 0, v[226:227]
	s_or_b64 exec, exec, s[16:17]
	v_lshl_add_u64 v[226:227], v[226:227], 0, v[144:145]
	global_load_dwordx4 v[208:211], v[226:227], off
	global_load_dwordx4 v[216:219], v[226:227], off offset:1024
	global_load_dwordx4 v[212:215], v[226:227], off offset:3072
	global_load_dwordx4 v[220:223], v[226:227], off offset:2048
	s_waitcnt vmcnt(0)
	s_branch .LBB0_32

; __device__ __forceinline__ unsigned pk2(float lo, float hi) { const f32x2v v = {lo, hi}; return __builtin_bit_cast(unsigned, __builtin_convertvector(v, bf16x2_hw)); }
; __device__ __forceinline__ void phase0(const Params& P, LAS unsigned char* lds, int G) {
;     ...
;         for (int row = gw; row < MT; row += NGW) {
;             const float* xr = row < MP ? xp + (size_t)row * DM : xs + (size_t)(row - MP) * DM;
;             f32x4v v[4]; float s = 0.f;
; #pragma unroll
;             for (int j = 0; j < 4; ++j) { v[j] = *(const f32x4v*)(xr + 256 * j + 4 * lane); s += (v[j][0] * v[j][0] + v[j][1] * v[j][1]) + (v[j][2] * v[j][2] + v[j][3] * v[j][3]); }
;             const float rs = 1.0f / sqrtf(wave_sum(s) * (1.0f / DM) + EPSN);
; #pragma unroll
;             for (int j = 0; j < 4; ++j) { v[j] = v[j] * rs; u32x2v w; w.x = pk2(v[j][0], v[j][1]); w.y = pk2(v[j][2], v[j][3]); *(u32x2v*)(XN + (size_t)row * DM + 256 * j + 4 * lane) = w; }
.LBB0_32:
	v_cmp_lt_i32_e32 vcc, s87, v162
	v_mov_b64_e32 v[164:165], v[162:163]
	s_waitcnt lgkmcnt(0)
	v_mov_b64_e32 v[128:129], v[160:161]
	s_and_saveexec_b64 s[16:17], vcc
	v_add_u32_e32 v128, 0xffffc000, v162
	v_mov_b32_e32 v129, v145
	v_lshlrev_b64 v[128:129], 12, v[128:129]
	v_lshl_add_u64 v[128:129], s[30:31], 0, v[128:129]
	v_mov_b32_e32 v164, v162
	v_mov_b32_e32 v165, v145
	s_or_b64 exec, exec, s[16:17]
	s_waitcnt vmcnt(5)
	v_mov_b32_e32 v128, v208
	v_mov_b32_e32 v129, v209
	v_mov_b32_e32 v130, v210
	v_mov_b32_e32 v131, v211
	v_mov_b32_e32 v132, v212
	v_mov_b32_e32 v133, v213
	v_mov_b32_e32 v134, v214
	v_mov_b32_e32 v135, v215
	v_mov_b32_e32 v136, v216
	v_mov_b32_e32 v137, v217
	v_mov_b32_e32 v138, v218
	v_mov_b32_e32 v139, v219
	v_mov_b32_e32 v140, v220
	v_mov_b32_e32 v141, v221
	v_mov_b32_e32 v142, v222
	v_mov_b32_e32 v143, v223
	v_lshl_add_u64 v[228:229], v[162:163], 0, s[34:35]
	s_movk_i32 s16, 0x401f
	v_cmp_ge_i32_e32 vcc, s16, v228
	s_and_saveexec_b64 s[72:73], vcc
	s_cbranch_execz .Lp0row_nopf
	v_lshl_add_u64 v[226:227], v[160:161], 0, s[56:57]
	v_cmp_lt_i32_e32 vcc, s87, v228
	s_and_saveexec_b64 s[16:17], vcc
	v_add_u32_e32 v226, 0xffffc000, v228
	v_mov_b32_e32 v227, v145
	v_lshlrev_b64 v[226:227], 12, v[226:227]
	v_lshl_add_u64 v[226:227], s[30:31], 0, v[226:227]
	s_or_b64 exec, exec, s[16:17]
	v_lshl_add_u64 v[226:227], v[226:227], 0, v[144:145]
	global_load_dwordx4 v[208:211], v[226:227], off
	global_load_dwordx4 v[216:219], v[226:227], off offset:1024
	global_load_dwordx4 v[212:215], v[226:227], off offset:3072
	global_load_dwordx4 v[220:223], v[226:227], off offset:2048
.Lp0row_nopf:
	s_or_b64 exec, exec, s[72:73]
	s_mov_b32 s16, 0xf800000
	v_pk_mul_f32 v[166:167], v[130:131], v[130:131]
	v_pk_mul_f32 v[168:169], v[128:129], v[128:129]
	v_pk_mul_f32 v[178:179], v[138:139], v[138:139]
	v_pk_mul_f32 v[186:187], v[136:137], v[136:137]
	v_pk_mov_b32 v[192:193], v[168:169], v[166:167] op_sel:[1,0]
	v_mov_b32_e32 v169, v167
	v_pk_mov_b32 v[166:167], v[186:187], v[178:179] op_sel:[1,0]
	v_mov_b32_e32 v187, v179
	v_mul_f32_e32 v191, v133, v133
	v_mul_f32_e32 v188, v141, v141
	v_mul_f32_e32 v190, v143, v143
	v_pk_add_f32 v[168:169], v[192:193], v[168:169]
	v_pk_add_f32 v[166:167], v[166:167], v[186:187]
	v_mul_f32_e32 v149, v132, v132
	v_mul_f32_e32 v194, v134, v134
	v_mul_f32_e32 v195, v135, v135
	v_pk_fma_f32 v[178:179], v[140:141], v[140:141], v[188:189] op_sel_hi:[1,1,0]
	v_pk_fma_f32 v[188:189], v[142:143], v[142:143], v[190:191] op_sel_hi:[1,1,0]
	v_pk_add_f32 v[168:169], v[168:169], v[168:169] op_sel:[0,1] op_sel_hi:[1,0]
	v_pk_add_f32 v[166:167], v[166:167], v[166:167] op_sel:[0,1] op_sel_hi:[1,0]
	v_mov_b32_e32 v179, v194
	v_mov_b32_e32 v189, v195
	v_mov_b32_e32 v169, v149
	v_mov_b32_e32 v167, v191
	v_pk_add_f32 v[178:179], v[178:179], v[188:189]
	v_pk_add_f32 v[166:167], v[168:169], v[166:167]
	s_nop 0
	v_pk_add_f32 v[166:167], v[166:167], v[178:179]
	s_nop 0
	v_add_f32_e32 v149, v166, v167
	ds_bpermute_b32 v166, v151, v149
	s_waitcnt lgkmcnt(0)
	v_add_f32_e32 v149, v149, v166
	ds_bpermute_b32 v166, v181, v149
	s_waitcnt lgkmcnt(0)
	v_add_f32_e32 v149, v149, v166
	ds_bpermute_b32 v166, v182, v149
	s_waitcnt lgkmcnt(0)
	v_add_f32_e32 v149, v149, v166
	ds_bpermute_b32 v166, v183, v149
	s_waitcnt lgkmcnt(0)
	v_add_f32_e32 v149, v149, v166
	ds_bpermute_b32 v166, v184, v149
	s_waitcnt lgkmcnt(0)
	v_add_f32_e32 v149, v149, v166
	ds_bpermute_b32 v166, v185, v149
	s_waitcnt lgkmcnt(0)
	v_add_f32_e32 v149, v149, v166
	v_fmamk_f32 v149, v149, 0x3a800000, v170
	v_mul_f32_e32 v166, 0x4f800000, v149
	v_cmp_gt_f32_e32 vcc, s16, v149
	s_nop 1
	v_cndmask_b32_e32 v149, v149, v166, vcc
	v_sqrt_f32_e32 v166, v149
	s_nop 0
	v_add_u32_e32 v167, -1, v166
	v_add_u32_e32 v168, 1, v166
	v_fma_f32 v169, -v167, v166, v149
	v_fma_f32 v178, -v168, v166, v149
	v_cmp_ge_f32_e64 s[16:17], 0, v169
	s_nop 1
	v_cndmask_b32_e64 v166, v166, v167, s[16:17]
	v_cmp_lt_f32_e64 s[16:17], 0, v178
	s_nop 1
	v_cndmask_b32_e64 v166, v166, v168, s[16:17]
	v_mul_f32_e32 v167, 0x37800000, v166
	v_cndmask_b32_e32 v166, v166, v167, vcc
	v_cmp_class_f32_e32 vcc, v149, v171
	s_nop 1
	v_cndmask_b32_e32 v149, v166, v149, vcc
	v_div_scale_f32 v166, s[16:17], v149, v149, 1.0
	v_rcp_f32_e32 v167, v166
	v_div_scale_f32 v168, vcc, 1.0, v149, 1.0
	v_fma_f32 v169, -v166, v167, 1.0
	v_fmac_f32_e32 v167, v169, v167
	v_mul_f32_e32 v169, v168, v167
	v_fma_f32 v178, -v166, v169, v168
	v_fmac_f32_e32 v169, v178, v167
	v_fma_f32 v166, -v166, v169, v168
	v_div_fmas_f32 v166, v166, v167, v169
	v_div_fixup_f32 v178, v166, v149, 1.0
	v_pk_mul_f32 v[130:131], v[130:131], v[178:179] op_sel_hi:[1,0]
	v_pk_mul_f32 v[166:167], v[128:129], v[178:179] op_sel_hi:[1,0]
	v_pk_mul_f32 v[128:129], v[138:139], v[178:179] op_sel_hi:[1,0]
	v_pk_mul_f32 v[168:169], v[136:137], v[178:179] op_sel_hi:[1,0]
	v_pk_mul_f32 v[136:137], v[142:143], v[178:179] op_sel_hi:[1,0]
	v_pk_mul_f32 v[138:139], v[140:141], v[178:179] op_sel_hi:[1,0]
	v_pk_mul_f32 v[134:135], v[134:135], v[178:179] op_sel_hi:[1,0]
	v_pk_mul_f32 v[132:133], v[132:133], v[178:179] op_sel_hi:[1,0]
	v_mul_f32_e32 v140, v1, v167
	v_mul_f32_e32 v141, v3, v131
	v_mul_f32_e32 v142, v5, v169
	v_mul_f32_e32 v143, v7, v129
	v_mul_f32_e32 v149, v9, v139
	v_mul_f32_e32 v178, v11, v137
	v_mul_f32_e32 v187, v17, v167
	v_mul_f32_e32 v188, v19, v131
	v_mul_f32_e32 v195, v167, v33
	v_mul_f32_e32 v196, v131, v35
	v_mul_f32_e32 v189, v21, v169
	v_mul_f32_e32 v190, v23, v129
	v_mul_f32_e32 v197, v169, v37
	v_mul_f32_e32 v198, v129, v39
	v_fmac_f32_e32 v140, v0, v166
	v_fmac_f32_e32 v141, v2, v130
	v_fmac_f32_e32 v142, v4, v168
	v_fmac_f32_e32 v143, v6, v128
; #define LAS __attribute__((address_space(3)))
; __device__ __forceinline__ void phase0(const Params& P, LAS unsigned char* lds, int G) {
;     ...
;             float d[8];
; #pragma unroll
;             for (int gi = 0; gi < 8; ++gi) {
;                 float s_ = 0.f;
; #pragma unroll
;                 for (int j = 0; j < 4; ++j) { const f32x4v w = *(const LAS f32x4v*)(wg + gi * 1024 + 256 * j + 4 * lane); s_ += (v[j][0] * w[0] + v[j][1] * w[1]) + (v[j][2] * w[2] + v[j][3] * w[3]); }
;                 d[gi] = s_;
;             }
;             { const bool b0 = lane & 1, b1 = lane & 2, b2 = lane & 4;
; #pragma unroll
;               for (int i = 0; i < 4; ++i) { const float snd = b0 ? d[i] : d[i + 4], kp = b0 ? d[i + 4] : d[i]; d[i] = kp + __shfl_xor(snd, 1); }
	v_fmac_f32_e32 v149, v8, v138
	v_fmac_f32_e32 v178, v10, v136
	v_fmac_f32_e32 v187, v16, v166
	v_fmac_f32_e32 v188, v18, v130
	v_fmac_f32_e32 v195, v166, v32
	v_fmac_f32_e32 v196, v130, v34
	v_mul_f32_e32 v199, v139, v41
	v_mul_f32_e32 v200, v137, v43
	v_fmac_f32_e32 v189, v20, v168
	v_fmac_f32_e32 v190, v22, v128
	v_fmac_f32_e32 v197, v168, v36
	v_fmac_f32_e32 v198, v128, v38
	v_add_f32_e32 v140, v140, v141
	v_add_f32_e32 v141, v142, v143
	v_add_f32_e32 v142, v149, v178
	v_add_f32_e32 v149, v187, v188
	v_add_f32_e32 v187, v195, v196
	v_mul_f32_e32 v179, v13, v133
	v_mul_f32_e32 v186, v15, v135
	v_fmac_f32_e32 v199, v138, v40
	v_fmac_f32_e32 v200, v136, v42
	v_add_f32_e32 v178, v189, v190
	v_add_f32_e32 v188, v197, v198
	v_add_f32_e32 v140, 0, v140
	v_add_f32_e32 v149, 0, v149
	v_add_f32_e32 v187, 0, v187
	v_mul_f32_e32 v203, v167, v49
	v_mul_f32_e32 v204, v131, v51
	v_fmac_f32_e32 v179, v12, v132
	v_fmac_f32_e32 v186, v14, v134
	v_add_f32_e32 v189, v199, v200
	v_add_f32_e32 v140, v141, v140
	v_add_f32_e32 v141, v178, v149
	v_add_f32_e32 v149, v187, v188
	v_fmac_f32_e32 v203, v166, v48
	v_add_f32_e32 v143, v179, v186
	v_add_f32_e32 v140, v142, v140
	v_add_f32_e32 v142, v149, v189
	v_fmac_f32_e32 v204, v130, v50
	v_mul_f32_e32 v149, v169, v53
	v_mul_f32_e32 v178, v129, v55
	v_add_f32_e32 v140, v143, v140
	v_add_f32_e32 v143, v203, v204
	v_fmac_f32_e32 v149, v168, v52
	v_fmac_f32_e32 v178, v128, v54
	v_add_f32_e32 v143, 0, v143
	v_add_f32_e32 v149, v149, v178
	v_add_f32_e32 v143, v143, v149
	v_mul_f32_e32 v149, v139, v57
	v_mul_f32_e32 v178, v137, v59
	v_fmac_f32_e32 v149, v138, v56
	v_fmac_f32_e32 v178, v136, v58
	v_add_f32_e32 v149, v149, v178
	v_add_f32_e32 v143, v143, v149
	v_mul_f32_e32 v149, v133, v61
	v_mul_f32_e32 v178, v135, v63
	v_fmac_f32_e32 v149, v132, v60
	v_fmac_f32_e32 v178, v134, v62
	v_mul_f32_e32 v191, v25, v139
	v_mul_f32_e32 v192, v27, v137
	v_add_f32_e32 v149, v149, v178
	v_fmac_f32_e32 v191, v24, v138
	v_fmac_f32_e32 v192, v26, v136
	v_add_f32_e32 v143, v143, v149
	v_mul_f32_e32 v149, v167, v65
	v_mul_f32_e32 v178, v131, v67
	v_add_f32_e32 v179, v191, v192
	v_fmac_f32_e32 v149, v166, v64
	v_fmac_f32_e32 v178, v130, v66
	v_add_f32_e32 v141, v179, v141
	v_add_f32_e32 v149, v149, v178
	v_mul_f32_e32 v178, v169, v69
	v_mul_f32_e32 v179, v129, v71
	v_fmac_f32_e32 v178, v168, v68
	v_fmac_f32_e32 v179, v128, v70
	v_add_f32_e32 v149, 0, v149
	v_add_f32_e32 v178, v178, v179
	v_add_f32_e32 v149, v149, v178
	v_mul_f32_e32 v178, v139, v73
	v_mul_f32_e32 v179, v137, v75
	v_fmac_f32_e32 v178, v138, v72
	v_fmac_f32_e32 v179, v136, v74
	v_add_f32_e32 v178, v178, v179
	v_add_f32_e32 v149, v149, v178
	v_mul_f32_e32 v178, v133, v77
	v_mul_f32_e32 v179, v135, v79
	v_fmac_f32_e32 v178, v132, v76
	v_fmac_f32_e32 v179, v134, v78
	v_mul_f32_e32 v193, v133, v29
	v_mul_f32_e32 v194, v135, v31
	v_add_f32_e32 v178, v178, v179
	v_fmac_f32_e32 v193, v132, v28
	v_fmac_f32_e32 v194, v134, v30
	v_add_f32_e32 v149, v149, v178
	v_mul_f32_e32 v178, v167, v81
	v_mul_f32_e32 v179, v131, v83
	v_add_f32_e32 v186, v193, v194
	v_fmac_f32_e32 v178, v166, v80
	v_fmac_f32_e32 v179, v130, v82
	v_add_f32_e32 v141, v186, v141
	v_add_f32_e32 v178, v178, v179
	v_mul_f32_e32 v179, v169, v85
	v_mul_f32_e32 v186, v129, v87
	v_fmac_f32_e32 v179, v168, v84
	v_fmac_f32_e32 v186, v128, v86
	v_add_f32_e32 v178, 0, v178
	v_add_f32_e32 v179, v179, v186
	v_add_f32_e32 v178, v178, v179
	v_mul_f32_e32 v179, v139, v89
	v_mul_f32_e32 v186, v137, v91
	v_fmac_f32_e32 v179, v138, v88
	v_fmac_f32_e32 v186, v136, v90
	v_add_f32_e32 v179, v179, v186
	v_add_f32_e32 v178, v178, v179
	v_mul_f32_e32 v179, v133, v93
	v_mul_f32_e32 v186, v135, v95
	v_fmac_f32_e32 v179, v132, v92
	v_fmac_f32_e32 v186, v134, v94
	v_add_f32_e32 v179, v179, v186
	v_add_f32_e32 v178, v178, v179
	v_mul_f32_e32 v179, v167, v97
	v_mul_f32_e32 v186, v131, v99
	v_fmac_f32_e32 v179, v166, v96
	v_fmac_f32_e32 v186, v130, v98
	v_add_f32_e32 v179, v179, v186
	v_mul_f32_e32 v186, v169, v101
	v_mul_f32_e32 v187, v129, v103
	v_fmac_f32_e32 v186, v168, v100
	v_fmac_f32_e32 v187, v128, v102
	v_add_f32_e32 v179, 0, v179
	v_add_f32_e32 v186, v186, v187
	v_add_f32_e32 v179, v179, v186
	v_mul_f32_e32 v186, v139, v105
	v_mul_f32_e32 v187, v137, v107
	v_fmac_f32_e32 v186, v138, v104
	v_fmac_f32_e32 v187, v136, v106
	v_add_f32_e32 v186, v186, v187
	v_add_f32_e32 v179, v179, v186
	v_mul_f32_e32 v186, v133, v109
	v_mul_f32_e32 v187, v135, v111
	v_fmac_f32_e32 v186, v132, v108
	v_fmac_f32_e32 v187, v134, v110
	v_add_f32_e32 v186, v186, v187
	v_add_f32_e32 v179, v179, v186
	v_mul_f32_e32 v186, v167, v113
	v_mul_f32_e32 v187, v131, v115
	v_fmac_f32_e32 v186, v166, v112
	v_fmac_f32_e32 v187, v130, v114
	v_add_f32_e32 v186, v186, v187
	v_mul_f32_e32 v187, v169, v117
	v_mul_f32_e32 v188, v129, v119
	v_fmac_f32_e32 v187, v168, v116
	v_fmac_f32_e32 v188, v128, v118
	v_add_f32_e32 v186, 0, v186
	v_add_f32_e32 v187, v187, v188
	v_add_f32_e32 v186, v186, v187
	v_mul_f32_e32 v187, v139, v121
	v_mul_f32_e32 v188, v137, v123
	v_fmac_f32_e32 v187, v138, v120
	v_fmac_f32_e32 v188, v136, v122
	v_mul_f32_e32 v201, v133, v45
	v_mul_f32_e32 v202, v135, v47
	v_add_f32_e32 v187, v187, v188
	v_fmac_f32_e32 v201, v132, v44
	v_fmac_f32_e32 v202, v134, v46
	v_add_f32_e32 v186, v186, v187
	v_mul_f32_e32 v187, v133, v125
	v_mul_f32_e32 v188, v135, v127
	v_add_f32_e32 v190, v201, v202
	v_fmac_f32_e32 v187, v132, v124
	v_fmac_f32_e32 v188, v134, v126
	v_add_f32_e32 v142, v142, v190
	v_add_f32_e32 v187, v187, v188
	v_cndmask_b32_e64 v189, v140, v149, s[4:5]
	v_add_f32_e32 v186, v186, v187
	v_cndmask_b32_e64 v140, v149, v140, s[4:5]
	v_cndmask_b32_e64 v149, v141, v178, s[4:5]
	v_cndmask_b32_e64 v141, v178, v141, s[4:5]
	v_cndmask_b32_e64 v178, v142, v179, s[4:5]
	ds_bpermute_b32 v189, v151, v189
	ds_bpermute_b32 v178, v151, v178
	v_cndmask_b32_e64 v187, v143, v186, s[4:5]
	ds_bpermute_b32 v149, v151, v149
	ds_bpermute_b32 v187, v151, v187
	v_cndmask_b32_e64 v142, v179, v142, s[4:5]
	s_waitcnt lgkmcnt(3)
; __device__ __forceinline__ float exp_(float x) { return __builtin_amdgcn_exp2f(x * LOG2E); }
; __device__ __forceinline__ void phase0(const Params& P, LAS unsigned char* lds, int G) {
;     ...
;             { const bool b0 = lane & 1, b1 = lane & 2, b2 = lane & 4;
; #pragma unroll
;               for (int i = 0; i < 4; ++i) { const float snd = b0 ? d[i] : d[i + 4], kp = b0 ? d[i + 4] : d[i]; d[i] = kp + __shfl_xor(snd, 1); }
; #pragma unroll
;               for (int i = 0; i < 2; ++i) { const float snd = b1 ? d[i] : d[i + 2], kp = b1 ? d[i + 2] : d[i]; d[i] = kp + __shfl_xor(snd, 2); }
;               { const float snd = b2 ? d[0] : d[1], kp = b2 ? d[1] : d[0]; d[0] = kp + __shfl_xor(snd, 4); }
;               d[0] += __shfl_xor(d[0], 8); d[0] += __shfl_xor(d[0], 16); d[0] += __shfl_xor(d[0], 32); }
;             if (lane < 8) {
;                 const int gidx = 4 * (lane & 1) + 2 * ((lane >> 1) & 1) + ((lane >> 2) & 1);
;                 const float mine = d[0];
;                 if (gidx < 4) GT[(size_t)row * 8 + gidx] = mine + b_ig[gidx];
;                 else { const float x = mine + b_fg[gidx - 4]; const float e = exp_(-fabsf(x));
;                     const float l1p = e < 0.02f ? e * (1.0f - e * (0.5f - e * (0.33333333f - 0.25f * e))) : __logf(1.0f + e);
;                     GT[(size_t)row * 8 + gidx] = fminf(x, 0.f) - l1p; }
	v_add_f32_e32 v140, v140, v189
	s_waitcnt lgkmcnt(2)
	v_add_f32_e32 v142, v142, v178
	v_cndmask_b32_e64 v143, v186, v143, s[4:5]
	s_waitcnt lgkmcnt(1)
	v_add_f32_e32 v141, v141, v149
	s_waitcnt lgkmcnt(0)
	v_add_f32_e32 v143, v143, v187
	v_cndmask_b32_e64 v149, v140, v142, s[6:7]
	ds_bpermute_b32 v149, v181, v149
	v_cndmask_b32_e64 v178, v141, v143, s[6:7]
	ds_bpermute_b32 v178, v181, v178
	v_cndmask_b32_e64 v140, v142, v140, s[6:7]
	s_waitcnt lgkmcnt(1)
	v_add_f32_e32 v142, v140, v149
	v_cndmask_b32_e64 v140, v143, v141, s[6:7]
	s_waitcnt lgkmcnt(0)
	v_add_f32_e32 v143, v140, v178
	v_cndmask_b32_e64 v140, v142, v143, s[8:9]
	ds_bpermute_b32 v149, v182, v140
	v_cndmask_b32_e64 v142, v143, v142, s[8:9]
	v_lshlrev_b64 v[140:141], 11, v[164:165]
	v_lshl_add_u64 v[140:141], v[152:153], 0, v[140:141]
	v_cvt_pk_bf16_f32 v143, v130, v131
	s_waitcnt lgkmcnt(0)
	v_add_f32_e32 v149, v142, v149
	ds_bpermute_b32 v178, v183, v149
	v_cvt_pk_bf16_f32 v142, v166, v167
	global_store_dwordx2 v[140:141], v[142:143], off
	v_cvt_pk_bf16_f32 v131, v128, v129
	v_cvt_pk_bf16_f32 v130, v168, v169
	s_waitcnt lgkmcnt(0)
	v_add_f32_e32 v142, v149, v178
	ds_bpermute_b32 v143, v184, v142
	global_store_dwordx2 v[140:141], v[130:131], off offset:512
	v_cvt_pk_bf16_f32 v130, v138, v139
	v_cvt_pk_bf16_f32 v131, v136, v137
	global_store_dwordx2 v[140:141], v[130:131], off offset:1024
	s_waitcnt lgkmcnt(0)
	v_add_f32_e32 v128, v142, v143
	ds_bpermute_b32 v129, v185, v128
	v_cvt_pk_bf16_f32 v130, v132, v133
	v_cvt_pk_bf16_f32 v131, v134, v135
	global_store_dwordx2 v[140:141], v[130:131], off offset:1536
	s_and_saveexec_b64 s[72:73], s[10:11]
	s_cbranch_execz .LBB0_31
	s_waitcnt lgkmcnt(0)
	v_add_f32_e32 v129, v128, v129
	s_and_saveexec_b64 s[16:17], s[12:13]
	s_xor_b64 s[74:75], exec, s[16:17]
	s_cbranch_execz .LBB0_41
	v_mov_b32_e32 v128, v224
	s_mov_b32 s16, 0xbfb8aa3b
	v_add_f32_e32 v128, v129, v128
	v_mul_f32_e64 v129, |v128|, s16
	v_exp_f32_e32 v130, v129
	s_mov_b32 s16, 0x3ca3d70a
	v_cmp_ngt_f32_e32 vcc, s16, v130
	s_and_saveexec_b64 s[16:17], vcc
	s_xor_b64 s[76:77], exec, s[16:17]
	s_cbranch_execz .LBB0_38
	v_add_f32_e32 v129, 1.0, v130
	s_mov_b32 s16, 0x800000
	v_cmp_gt_f32_e32 vcc, s16, v129
	s_mov_b32 s16, 0x3f317217
	s_nop 0
	v_cndmask_b32_e64 v130, 0, 32, vcc
	v_ldexp_f32 v129, v129, v130
	v_log_f32_e32 v129, v129
	s_nop 0
	v_mul_f32_e32 v130, 0x3f317217, v129
	v_fma_f32 v130, v129, s16, -v130
	v_fmac_f32_e32 v130, 0x3377d1cf, v129
	s_mov_b32 s16, 0x7f800000
	v_fmac_f32_e32 v130, 0x3f317217, v129
	v_cmp_lt_f32_e64 s[16:17], |v129|, s16
	s_nop 1
	v_cndmask_b32_e64 v129, v129, v130, s[16:17]
	v_cndmask_b32_e32 v130, 0, v175, vcc
	v_sub_f32_e32 v129, v129, v130

; __device__ __forceinline__ void phase0(const Params& P, LAS unsigned char* lds, int G) {
;     ...
;             if (lane < 8) {
;                 const int gidx = 4 * (lane & 1) + 2 * ((lane >> 1) & 1) + ((lane >> 2) & 1);
;                 const float mine = d[0];
;                 if (gidx < 4) GT[(size_t)row * 8 + gidx] = mine + b_ig[gidx];
.LBB0_41:
	s_andn2_saveexec_b64 s[16:17], s[74:75]
	s_cbranch_execz .LBB0_30
	v_mov_b32_e32 v128, v225
	v_add_f32_e32 v128, v129, v128
	s_branch .LBB0_30
